# v014
# speedup vs baseline: 1.0301x; 1.0159x over previous
; __device__ __forceinline__ float lo16(unsigned u) { return __uint_as_float(u << 16); }
; __device__ __forceinline__ float hi16(unsigned u) { return __uint_as_float(u & 0xffff0000u); }
; __device__ __forceinline__ void scan_item(cchar4* ka, int L, int item, char* smem) {
;     ...
;   auto gload = [&](int chunk) {
;     int s = chunk * 32 + lstep;
;     int t = dir ? (2047 - s) : s;
;     size_t tok = (size_t)b * 2048 + t;
;     size_t o5 = tok * 512 + h * 64 + lc4;
;     size_t o10 = tok * 1024 + dir * 512 + h * 64 + lc4;
;     gr = *(const uint2*)(Rb + o5); gk = *(const uint2*)(Kb + o5); gv = *(const uint2*)(Vb + o5);
;     gkk = *(const uint2*)(KKb + o5); ge = *(const uint2*)(Eb + o10); ga = *(const uint2*)(AAb + o10);
;   };
;   auto lwrite = [&](int bi) {
;     float* dst = buf + ((size_t)(bi * 32 + lstep) * 6) * 64 + lc4;
;     float r4[4] = {lo16(gr.x), hi16(gr.x), lo16(gr.y), hi16(gr.y)};
;     float k4[4] = {lo16(gk.x), hi16(gk.x), lo16(gk.y), hi16(gk.y)};
;     float v4[4] = {lo16(gv.x), hi16(gv.x), lo16(gv.y), hi16(gv.y)};
;     float kk4[4] = {lo16(gkk.x), hi16(gkk.x), lo16(gkk.y), hi16(gkk.y)};
;     float e4[4] = {lo16(ge.x), hi16(ge.x), lo16(ge.y), hi16(ge.y)};
;     float a4[4] = {lo16(ga.x), hi16(ga.x), lo16(ga.y), hi16(ga.y)};
;     float4 w, kka, kd;
;     w.x = __expf(-e4[0]); w.y = __expf(-e4[1]); w.z = __expf(-e4[2]); w.w = __expf(-e4[3]);
;     kka.x = kk4[0] * a4[0]; kka.y = kk4[1] * a4[1]; kka.z = kk4[2] * a4[2]; kka.w = kk4[3] * a4[3];
;     kd.x = k4[0] * (1.f + (a4[0] - 1.f) * ka4[0]); kd.y = k4[1] * (1.f + (a4[1] - 1.f) * ka4[1]);
;     kd.z = k4[2] * (1.f + (a4[2] - 1.f) * ka4[2]); kd.w = k4[3] * (1.f + (a4[3] - 1.f) * ka4[3]);
;     *(float4*)(dst + 0 * 64) = w;
;     *(float4*)(dst + 1 * 64) = make_float4(kk4[0], kk4[1], kk4[2], kk4[3]);
;     *(float4*)(dst + 2 * 64) = kka;
;     *(float4*)(dst + 3 * 64) = kd;
;     *(float4*)(dst + 4 * 64) = make_float4(r4[0], r4[1], r4[2], r4[3]);
;     *(float4*)(dst + 5 * 64) = make_float4(v4[0], v4[1], v4[2], v4[3]);
;   };
;   __syncthreads();
;   gload(0); lwrite(0);
;   __syncthreads();
;   typedef float f2v __attribute__((ext_vector_type(2)));
;   f2v st2[4];
; #pragma unroll
;   for (int i = 0; i < 4; ++i) st2[i] = f2v{0.f, 0.f};
.LBB0_2445:
	s_andn2_b64 vcc, exec, s[6:7]
	s_cbranch_vccnz .LBB0_2460
	v_readlane_b32 s2, v255, 24
	v_readlane_b32 s3, v255, 25
	s_load_dwordx2 s[2:3], s[2:3], 0x78
	s_add_i32 s13, s57, s15
	s_ashr_i32 s8, s13, 6
	v_readlane_b32 s10, v255, 26
	s_ashr_i32 s9, s8, 31
	v_readlane_b32 s11, v255, 27
	s_bfe_u32 s12, s13, 0x30003
	s_lshl_b64 s[6:7], s[8:9], 25
	s_lshl_b64 s[10:11], s[10:11], 2
	s_waitcnt lgkmcnt(0)
	s_add_u32 s2, s2, s10
	v_mov_b32_e32 v26, v176
	s_addc_u32 s9, s3, s11
	s_lshl_b32 s3, s57, 6
	s_and_b32 s16, s3, 0x1c0
	v_lshrrev_b32_e32 v0, 3, v26
	v_ashrrev_i32_e32 v28, 3, v26
	v_and_b32_e32 v0, 6, v0
	s_lshl_b32 s3, s16, 2
	v_and_or_b32 v44, v28, -8, v0
	v_lshlrev_b32_e32 v0, 2, v26
	s_add_u32 s10, s2, s3
	v_and_b32_e32 v6, 60, v0
	s_addc_u32 s11, s9, 0
	v_lshlrev_b32_e32 v61, 2, v6
	global_load_dwordx4 v[0:3], v61, s[10:11]
	s_add_u32 s10, s50, s6
	s_addc_u32 s11, s39, s7
	v_ashrrev_i32_e32 v78, 4, v26
	s_cmp_lt_u32 s13, 64
	s_cselect_b64 s[6:7], -1, 0
	v_sub_u32_e32 v4, 0x7ff, v78
	v_cndmask_b32_e64 v4, v4, v78, s[6:7]
	s_lshl_b32 s34, s12, 11
	v_ashrrev_i32_e32 v5, 31, v4
	s_lshl_b32 s8, s8, 9
	v_lshl_add_u64 v[4:5], s[34:35], 0, v[4:5]
	v_or_b32_e32 v46, s16, v6
	s_ashr_i32 s9, s8, 31
	v_lshlrev_b64 v[4:5], 10, v[4:5]
	v_or_b32_e32 v48, s8, v46
	v_mov_b32_e32 v49, s9
	v_lshl_add_u64 v[6:7], v[4:5], 0, v[48:49]
	v_lshl_or_b32 v4, v46, 1, v4
	v_lshl_add_u64 v[8:9], s[28:29], 0, v[4:5]
	s_barrier
	global_load_dwordx2 v[50:51], v[8:9], off
	v_lshl_add_u64 v[8:9], s[22:23], 0, v[4:5]
	global_load_dwordx2 v[52:53], v[8:9], off
	v_lshl_add_u64 v[8:9], s[30:31], 0, v[4:5]
	v_lshl_add_u64 v[4:5], s[24:25], 0, v[4:5]
	global_load_dwordx2 v[54:55], v[8:9], off
	global_load_dwordx2 v[56:57], v[4:5], off
	v_lshlrev_b64 v[4:5], 1, v[6:7]
	v_lshl_add_u64 v[6:7], s[36:37], 0, v[4:5]
	global_load_dwordx2 v[58:59], v[6:7], off
	v_lshl_add_u64 v[4:5], s[26:27], 0, v[4:5]
	global_load_dwordx2 v[12:13], v[4:5], off
	s_movk_i32 s8, 0x600
	v_mul_lo_u32 v4, v78, s8
	v_or_b32_e32 v29, v61, v4
	s_add_u32 s10, s10, s3
	v_and_b32_e32 v27, 15, v26
	v_ashrrev_i32_e32 v45, 31, v44
	s_addc_u32 s11, s11, 0
	v_lshlrev_b32_e32 v178, 2, v27
	s_lshl_b32 s33, s12, 20
	s_movk_i32 s12, 0xffe0
	v_mov_b32_e32 v64, 0
	s_movk_i32 s2, 0x7ff
	v_cmp_gt_u32_e64 s[8:9], 2, v27
	s_mov_b32 s3, 0
	s_mov_b32 s44, s35
	s_mov_b32 s16, 0
	v_mov_b32_e32 v65, v64
	v_mov_b32_e32 v66, v64
	v_mov_b32_e32 v67, v64
	v_mov_b32_e32 v68, v64
	v_mov_b32_e32 v69, v64
	v_mov_b32_e32 v70, v64
	v_mov_b32_e32 v71, v64
	s_waitcnt vmcnt(5)
	v_lshlrev_b32_e32 v8, 16, v50
	v_and_b32_e32 v9, 0xffff0000, v50
	v_lshlrev_b32_e32 v10, 16, v51
	v_and_b32_e32 v11, 0xffff0000, v51
	s_waitcnt vmcnt(3)
	v_lshlrev_b32_e32 v4, 16, v54
	s_waitcnt vmcnt(2)
	v_lshlrev_b32_e32 v14, 16, v56
	v_and_b32_e32 v15, 0xffff0000, v56
	v_and_b32_e32 v5, 0xffff0000, v54
	s_waitcnt vmcnt(1)
	v_lshlrev_b32_e32 v16, 16, v58
	v_and_b32_e32 v17, 0xffff0000, v58
	v_lshlrev_b32_e32 v18, 16, v59
	v_and_b32_e32 v19, 0xffff0000, v59
	v_mul_f32_e32 v16, 0xbfb8aa3b, v16
	v_mul_f32_e32 v17, 0xbfb8aa3b, v17
	v_mul_f32_e32 v18, 0xbfb8aa3b, v18
	v_mul_f32_e32 v19, 0xbfb8aa3b, v19
	v_exp_f32_e32 v16, v16
	v_exp_f32_e32 v17, v17
	v_exp_f32_e32 v18, v18
	v_exp_f32_e32 v19, v19
	s_waitcnt vmcnt(0)
	v_lshlrev_b32_e32 v22, 16, v12
	v_and_b32_e32 v23, 0xffff0000, v12
	v_lshlrev_b32_e32 v24, 16, v13
	ds_write_b128 v29, v[16:19]
	v_lshlrev_b32_e32 v16, 16, v57
	v_and_b32_e32 v17, 0xffff0000, v57
	v_and_b32_e32 v25, 0xffff0000, v13
	v_pk_mul_f32 v[18:19], v[14:15], v[22:23]
	v_pk_mul_f32 v[20:21], v[16:17], v[24:25]
	ds_write_b128 v29, v[14:17] offset:256
	ds_write_b128 v29, v[18:21] offset:512
	v_pk_add_f32 v[16:17], v[22:23], -1.0 op_sel_hi:[1,0]
	v_lshlrev_b32_e32 v14, 16, v52
	v_and_b32_e32 v15, 0xffff0000, v52
	v_pk_fma_f32 v[16:17], v[0:1], v[16:17], 1.0 op_sel_hi:[1,1,0]
	v_pk_add_f32 v[18:19], v[24:25], -1.0 op_sel_hi:[1,0]
	v_pk_mul_f32 v[14:15], v[16:17], v[14:15]
	v_lshlrev_b32_e32 v16, 16, v53
	v_and_b32_e32 v17, 0xffff0000, v53
	v_pk_fma_f32 v[18:19], v[2:3], v[18:19], 1.0 op_sel_hi:[1,1,0]
	v_lshlrev_b32_e32 v6, 16, v55
	v_pk_mul_f32 v[16:17], v[18:19], v[16:17]
	v_and_b32_e32 v7, 0xffff0000, v55
	ds_write_b128 v29, v[14:17] offset:768
	ds_write_b128 v29, v[8:11] offset:1024
	ds_write_b128 v29, v[4:7] offset:1280
	v_lshl_add_u64 v[4:5], v[44:45], 2, s[10:11]
	v_lshl_add_u64 v[62:63], v[4:5], 0, v[178:179]
	v_lshrrev_b32_e32 v5, 1, v26
	v_lshlrev_b32_e32 v4, 2, v28
	v_and_b32_e32 v5, 24, v5
	v_lshlrev_b32_e32 v45, 4, v27
	v_and_or_b32 v4, v4, s12, v5
	v_mov_b32_e32 v60, v57
	v_mov_b32_e32 v47, v13
	v_cmp_eq_u32_e64 s[10:11], 0, v27
	v_add_u32_e32 v79, 0xb00, v4
	v_mov_b32_e32 v80, 0
	v_mov_b32_e32 v81, 0
	v_mov_b32_e32 v82, 0
	v_mov_b32_e32 v83, 0
	v_mov_b32_e32 v84, 0
	v_mov_b32_e32 v85, 0
	v_mov_b32_e32 v86, 0
	v_mov_b32_e32 v87, 0
	s_mov_b64 s[12:13], 0
	v_mov_b32_e32 v57, v12
	s_waitcnt lgkmcnt(0)
	s_barrier
	s_branch .LBB0_2448

; #define SC_LOAD(P, s_) do { const float* _sb = cb + (s_) * 384; \
;       P##w = *(const float4*)(_sb); P##q = *(const float4*)(_sb + 64); P##a = *(const float4*)(_sb + 128); \
;       P##d = *(const float4*)(_sb + 192); P##r = *(const float4*)(_sb + 256); \
;       P##vv = *(const float2*)(cv + (s_) * 384); } while (0)
; __device__ __forceinline__ void scan_item(cchar4* ka, int L, int item, char* smem) {
;     ...
;     SC_LOAD(c, 0);
;     for (int s = 0; s < 32; s += 2) {
;       SC_LOAD(n, s + 1);
;       SC_STEP(c, s);
;       if (s + 2 < 32) SC_LOAD(c, s + 2);
;       SC_STEP(n, s + 1);
.LBB0_2450:
	v_readfirstlane_b32 s17, v176
	s_lshl_b32 s16, s16, 5
	s_and_b32 s16, s16, 32
	s_mulk_i32 s16, 0x600
	s_cmpk_gt_u32 s17, 0xff
	s_cbranch_scc1 .LBB0_2458
	v_and_b32_e32 v20, 7, v176
	v_lshrrev_b32_e32 v21, 2, v176
	v_and_b32_e32 v21, 0xfffffffe, v21
	v_lshl_add_u32 v20, v20, 5, s16
	v_sub_u32_e32 v38, v21, v44
	v_lshrrev_b32_e32 v39, 2, v45
	v_lshlrev_b32_e32 v38, 2, v38
	v_sub_u32_e32 v38, v38, v39
	v_ashrrev_i32_e32 v39, 31, v38
	v_lshl_add_u32 v21, v21, 2, s16
	v_lshl_add_u64 v[40:41], v[38:39], 0, v[62:63]
	s_and_b64 s[48:49], s[6:7], exec
	s_cselect_b32 s46, s3, s2
	s_cselect_b32 s47, 1, -1
	s_mov_b32 s49, 0
	s_movk_i32 s17, 16
	ds_read_b128 v[88:91], v20 offset:0
	ds_read_b128 v[92:95], v20 offset:16
	ds_read_b128 v[96:99], v20 offset:256
	ds_read_b128 v[100:103], v20 offset:272
	ds_read_b128 v[104:107], v20 offset:512
	ds_read_b128 v[108:111], v20 offset:528
	ds_read_b128 v[112:115], v20 offset:768
	ds_read_b128 v[116:119], v20 offset:784
	ds_read_b128 v[120:123], v20 offset:1024
	ds_read_b128 v[124:127], v20 offset:1040
	ds_read_b64 v[128:129], v21 offset:1280
.Lscan_step_loop:
	s_waitcnt lgkmcnt(0)
	ds_read_b128 v[132:135], v20 offset:1536
	ds_read_b128 v[136:139], v20 offset:1552
	ds_read_b128 v[140:143], v20 offset:1792
	ds_read_b128 v[144:147], v20 offset:1808
	ds_read_b128 v[148:151], v20 offset:2048
	ds_read_b128 v[152:155], v20 offset:2064
	ds_read_b128 v[156:159], v20 offset:2304
	ds_read_b128 v[160:163], v20 offset:2320
	ds_read_b128 v[164:167], v20 offset:2560
	ds_read_b128 v[168:171], v20 offset:2576
	ds_read_b64 v[172:173], v21 offset:2816
	v_pk_mul_f32 v[4:5], v[64:65], v[96:97]
	v_pk_mul_f32 v[6:7], v[80:81], v[96:97]
	v_pk_fma_f32 v[4:5], v[66:67], v[98:99], v[4:5]
	v_pk_fma_f32 v[6:7], v[82:83], v[98:99], v[6:7]
	v_pk_fma_f32 v[4:5], v[68:69], v[100:101], v[4:5]
	v_pk_fma_f32 v[6:7], v[84:85], v[100:101], v[6:7]
	v_pk_fma_f32 v[4:5], v[70:71], v[102:103], v[4:5]
	v_pk_fma_f32 v[6:7], v[86:87], v[102:103], v[6:7]
	v_pk_mul_f32 v[12:13], v[112:113], v[128:129] op_sel_hi:[1,0]
	v_add_f32_e32 v8, v4, v5
	v_add_f32_e32 v10, v6, v7
	v_pk_mul_f32 v[24:25], v[112:113], v[128:129] op_sel:[0,1]
	v_pk_mul_f32 v[14:15], v[114:115], v[128:129] op_sel_hi:[1,0]
	v_add_f32_dpp v8, v8, v8 quad_perm:[1,0,3,2] row_mask:0xf bank_mask:0xf bound_ctrl:1
	v_add_f32_dpp v10, v10, v10 quad_perm:[1,0,3,2] row_mask:0xf bank_mask:0xf bound_ctrl:1
	v_pk_mul_f32 v[26:27], v[114:115], v[128:129] op_sel:[0,1]
	v_add_f32_dpp v8, v8, v8 quad_perm:[2,3,0,1] row_mask:0xf bank_mask:0xf bound_ctrl:1
	v_add_f32_dpp v10, v10, v10 quad_perm:[2,3,0,1] row_mask:0xf bank_mask:0xf bound_ctrl:1
	v_pk_mul_f32 v[16:17], v[116:117], v[128:129] op_sel_hi:[1,0]
	v_add_f32_dpp v8, v8, v8 row_half_mirror row_mask:0xf bank_mask:0xf bound_ctrl:1
	v_add_f32_dpp v10, v10, v10 row_half_mirror row_mask:0xf bank_mask:0xf bound_ctrl:1
	v_pk_mul_f32 v[28:29], v[116:117], v[128:129] op_sel:[0,1]
	v_pk_mul_f32 v[18:19], v[118:119], v[128:129] op_sel_hi:[1,0]
	v_pk_mul_f32 v[30:31], v[118:119], v[128:129] op_sel:[0,1]
	v_pk_fma_f32 v[12:13], v[8:9], v[104:105], v[12:13] op_sel_hi:[0,1,1] neg_lo:[1,0,0] neg_hi:[1,0,0]
	v_pk_fma_f32 v[24:25], v[10:11], v[104:105], v[24:25] op_sel_hi:[0,1,1] neg_lo:[1,0,0] neg_hi:[1,0,0]
	v_pk_fma_f32 v[14:15], v[8:9], v[106:107], v[14:15] op_sel_hi:[0,1,1] neg_lo:[1,0,0] neg_hi:[1,0,0]
	v_pk_fma_f32 v[26:27], v[10:11], v[106:107], v[26:27] op_sel_hi:[0,1,1] neg_lo:[1,0,0] neg_hi:[1,0,0]
	v_pk_fma_f32 v[16:17], v[8:9], v[108:109], v[16:17] op_sel_hi:[0,1,1] neg_lo:[1,0,0] neg_hi:[1,0,0]
	v_pk_fma_f32 v[28:29], v[10:11], v[108:109], v[28:29] op_sel_hi:[0,1,1] neg_lo:[1,0,0] neg_hi:[1,0,0]
	v_pk_fma_f32 v[18:19], v[8:9], v[110:111], v[18:19] op_sel_hi:[0,1,1] neg_lo:[1,0,0] neg_hi:[1,0,0]
	v_pk_fma_f32 v[30:31], v[10:11], v[110:111], v[30:31] op_sel_hi:[0,1,1] neg_lo:[1,0,0] neg_hi:[1,0,0]
	v_pk_fma_f32 v[64:65], v[64:65], v[88:89], v[12:13]
	v_pk_fma_f32 v[80:81], v[80:81], v[88:89], v[24:25]
	v_pk_fma_f32 v[66:67], v[66:67], v[90:91], v[14:15]
	v_pk_fma_f32 v[82:83], v[82:83], v[90:91], v[26:27]
	v_pk_fma_f32 v[68:69], v[68:69], v[92:93], v[16:17]
	v_pk_fma_f32 v[84:85], v[84:85], v[92:93], v[28:29]
	v_pk_fma_f32 v[70:71], v[70:71], v[94:95], v[18:19]
	v_pk_fma_f32 v[86:87], v[86:87], v[94:95], v[30:31]
	v_pk_mul_f32 v[32:33], v[64:65], v[120:121]
	v_pk_mul_f32 v[34:35], v[80:81], v[120:121]
	v_pk_fma_f32 v[32:33], v[66:67], v[122:123], v[32:33]
	v_pk_fma_f32 v[34:35], v[82:83], v[122:123], v[34:35]
	v_pk_fma_f32 v[32:33], v[68:69], v[124:125], v[32:33]
	v_pk_fma_f32 v[34:35], v[84:85], v[124:125], v[34:35]
	v_pk_fma_f32 v[32:33], v[70:71], v[126:127], v[32:33]
	v_pk_fma_f32 v[34:35], v[86:87], v[126:127], v[34:35]
	s_lshl_b32 s48, s46, 9
	v_add_f32_e32 v36, v32, v33
	v_add_f32_e32 v37, v34, v35
	s_or_b32 s48, s33, s48
	s_add_i32 s46, s46, s47
	v_add_f32_dpp v36, v36, v36 quad_perm:[1,0,3,2] row_mask:0xf bank_mask:0xf bound_ctrl:1
	v_add_f32_dpp v37, v37, v37 quad_perm:[1,0,3,2] row_mask:0xf bank_mask:0xf bound_ctrl:1
	v_lshl_add_u64 v[42:43], s[48:49], 2, v[40:41]
	v_add_f32_dpp v36, v36, v36 quad_perm:[2,3,0,1] row_mask:0xf bank_mask:0xf bound_ctrl:1
	v_add_f32_dpp v37, v37, v37 quad_perm:[2,3,0,1] row_mask:0xf bank_mask:0xf bound_ctrl:1
	s_nop 0
	v_add_f32_dpp v36, v36, v36 row_half_mirror row_mask:0xf bank_mask:0xf bound_ctrl:1
	v_add_f32_dpp v37, v37, v37 row_half_mirror row_mask:0xf bank_mask:0xf bound_ctrl:1
	s_mov_b32 exec_lo, 0x1010101
	s_mov_b32 exec_hi, 0x1010101
	global_store_dwordx2 v[42:43], v[36:37], off
	s_mov_b64 exec, -1
	s_waitcnt lgkmcnt(0)
; #define SC_LOAD(P, s_) do { const float* _sb = cb + (s_) * 384; \
;       P##w = *(const float4*)(_sb); P##q = *(const float4*)(_sb + 64); P##a = *(const float4*)(_sb + 128); \
;       P##d = *(const float4*)(_sb + 192); P##r = *(const float4*)(_sb + 256); \
;       P##vv = *(const float2*)(cv + (s_) * 384); } while (0)
; __device__ __forceinline__ void scan_item(cchar4* ka, int L, int item, char* smem) {
;     ...
;     SC_LOAD(c, 0);
;     for (int s = 0; s < 32; s += 2) {
;       SC_LOAD(n, s + 1);
;       SC_STEP(c, s);
;       if (s + 2 < 32) SC_LOAD(c, s + 2);
;       SC_STEP(n, s + 1);
	ds_read_b128 v[88:91], v20 offset:3072
	ds_read_b128 v[92:95], v20 offset:3088
	ds_read_b128 v[96:99], v20 offset:3328
	ds_read_b128 v[100:103], v20 offset:3344
	ds_read_b128 v[104:107], v20 offset:3584
	ds_read_b128 v[108:111], v20 offset:3600
	ds_read_b128 v[112:115], v20 offset:3840
	ds_read_b128 v[116:119], v20 offset:3856
	ds_read_b128 v[120:123], v20 offset:4096
	ds_read_b128 v[124:127], v20 offset:4112
	ds_read_b64 v[128:129], v21 offset:4352
	v_pk_mul_f32 v[4:5], v[64:65], v[140:141]
	v_pk_mul_f32 v[6:7], v[80:81], v[140:141]
	v_pk_fma_f32 v[4:5], v[66:67], v[142:143], v[4:5]
	v_pk_fma_f32 v[6:7], v[82:83], v[142:143], v[6:7]
	v_pk_fma_f32 v[4:5], v[68:69], v[144:145], v[4:5]
	v_pk_fma_f32 v[6:7], v[84:85], v[144:145], v[6:7]
	v_pk_fma_f32 v[4:5], v[70:71], v[146:147], v[4:5]
	v_pk_fma_f32 v[6:7], v[86:87], v[146:147], v[6:7]
	v_pk_mul_f32 v[12:13], v[156:157], v[172:173] op_sel_hi:[1,0]
	v_add_f32_e32 v8, v4, v5
	v_add_f32_e32 v10, v6, v7
	v_pk_mul_f32 v[24:25], v[156:157], v[172:173] op_sel:[0,1]
	v_pk_mul_f32 v[14:15], v[158:159], v[172:173] op_sel_hi:[1,0]
	v_add_f32_dpp v8, v8, v8 quad_perm:[1,0,3,2] row_mask:0xf bank_mask:0xf bound_ctrl:1
	v_add_f32_dpp v10, v10, v10 quad_perm:[1,0,3,2] row_mask:0xf bank_mask:0xf bound_ctrl:1
	v_pk_mul_f32 v[26:27], v[158:159], v[172:173] op_sel:[0,1]
	v_add_f32_dpp v8, v8, v8 quad_perm:[2,3,0,1] row_mask:0xf bank_mask:0xf bound_ctrl:1
	v_add_f32_dpp v10, v10, v10 quad_perm:[2,3,0,1] row_mask:0xf bank_mask:0xf bound_ctrl:1
	v_pk_mul_f32 v[16:17], v[160:161], v[172:173] op_sel_hi:[1,0]
	v_add_f32_dpp v8, v8, v8 row_half_mirror row_mask:0xf bank_mask:0xf bound_ctrl:1
	v_add_f32_dpp v10, v10, v10 row_half_mirror row_mask:0xf bank_mask:0xf bound_ctrl:1
	v_pk_mul_f32 v[28:29], v[160:161], v[172:173] op_sel:[0,1]
	v_pk_mul_f32 v[18:19], v[162:163], v[172:173] op_sel_hi:[1,0]
	v_pk_mul_f32 v[30:31], v[162:163], v[172:173] op_sel:[0,1]
	v_pk_fma_f32 v[12:13], v[8:9], v[148:149], v[12:13] op_sel_hi:[0,1,1] neg_lo:[1,0,0] neg_hi:[1,0,0]
	v_pk_fma_f32 v[24:25], v[10:11], v[148:149], v[24:25] op_sel_hi:[0,1,1] neg_lo:[1,0,0] neg_hi:[1,0,0]
	v_pk_fma_f32 v[14:15], v[8:9], v[150:151], v[14:15] op_sel_hi:[0,1,1] neg_lo:[1,0,0] neg_hi:[1,0,0]
	v_pk_fma_f32 v[26:27], v[10:11], v[150:151], v[26:27] op_sel_hi:[0,1,1] neg_lo:[1,0,0] neg_hi:[1,0,0]
	v_pk_fma_f32 v[16:17], v[8:9], v[152:153], v[16:17] op_sel_hi:[0,1,1] neg_lo:[1,0,0] neg_hi:[1,0,0]
	v_pk_fma_f32 v[28:29], v[10:11], v[152:153], v[28:29] op_sel_hi:[0,1,1] neg_lo:[1,0,0] neg_hi:[1,0,0]
	v_pk_fma_f32 v[18:19], v[8:9], v[154:155], v[18:19] op_sel_hi:[0,1,1] neg_lo:[1,0,0] neg_hi:[1,0,0]
	v_pk_fma_f32 v[30:31], v[10:11], v[154:155], v[30:31] op_sel_hi:[0,1,1] neg_lo:[1,0,0] neg_hi:[1,0,0]
	v_pk_fma_f32 v[64:65], v[64:65], v[132:133], v[12:13]
	v_pk_fma_f32 v[80:81], v[80:81], v[132:133], v[24:25]
	v_pk_fma_f32 v[66:67], v[66:67], v[134:135], v[14:15]
	v_pk_fma_f32 v[82:83], v[82:83], v[134:135], v[26:27]
	v_pk_fma_f32 v[68:69], v[68:69], v[136:137], v[16:17]
	v_pk_fma_f32 v[84:85], v[84:85], v[136:137], v[28:29]
	v_pk_fma_f32 v[70:71], v[70:71], v[138:139], v[18:19]
	v_pk_fma_f32 v[86:87], v[86:87], v[138:139], v[30:31]
	v_pk_mul_f32 v[32:33], v[64:65], v[164:165]
	v_pk_mul_f32 v[34:35], v[80:81], v[164:165]
	v_pk_fma_f32 v[32:33], v[66:67], v[166:167], v[32:33]
	v_pk_fma_f32 v[34:35], v[82:83], v[166:167], v[34:35]
	v_pk_fma_f32 v[32:33], v[68:69], v[168:169], v[32:33]
	v_pk_fma_f32 v[34:35], v[84:85], v[168:169], v[34:35]
	v_pk_fma_f32 v[32:33], v[70:71], v[170:171], v[32:33]
	v_pk_fma_f32 v[34:35], v[86:87], v[170:171], v[34:35]
	s_lshl_b32 s48, s46, 9
	v_add_f32_e32 v36, v32, v33
	v_add_f32_e32 v37, v34, v35
	s_or_b32 s48, s33, s48
	s_add_i32 s46, s46, s47
	v_add_f32_dpp v36, v36, v36 quad_perm:[1,0,3,2] row_mask:0xf bank_mask:0xf bound_ctrl:1
	v_add_f32_dpp v37, v37, v37 quad_perm:[1,0,3,2] row_mask:0xf bank_mask:0xf bound_ctrl:1
	v_lshl_add_u64 v[42:43], s[48:49], 2, v[40:41]
	v_add_f32_dpp v36, v36, v36 quad_perm:[2,3,0,1] row_mask:0xf bank_mask:0xf bound_ctrl:1
	v_add_f32_dpp v37, v37, v37 quad_perm:[2,3,0,1] row_mask:0xf bank_mask:0xf bound_ctrl:1
	s_nop 0
	v_add_f32_dpp v36, v36, v36 row_half_mirror row_mask:0xf bank_mask:0xf bound_ctrl:1
	v_add_f32_dpp v37, v37, v37 row_half_mirror row_mask:0xf bank_mask:0xf bound_ctrl:1
	s_mov_b32 exec_lo, 0x1010101
	s_mov_b32 exec_hi, 0x1010101
	global_store_dwordx2 v[42:43], v[36:37], off
	s_mov_b64 exec, -1
	v_add_u32_e32 v20, 0xc00, v20
	v_add_u32_e32 v21, 0xc00, v21
	s_add_i32 s17, s17, -1
	s_cmp_lg_u32 s17, 0
	s_cbranch_scc1 .Lscan_step_loop
